# epilogue loads batched: resid xb rows and inproj gains issued together with counted waits
# speedup vs baseline: 1.0230x; 1.0069x over previous
; DI unsigned pack2(float a, float b) { f32x2_t v = {a, b}; bf16x2_t r = __builtin_convertvector(v, bf16x2_t); return __builtin_bit_cast(unsigned, r); }
; DI float xor32(float v) { return __shfl_xor(v, 32); }
; DI bool epi_inproj_chunk(const P& p, int layer, int ch, int m0w, f32x16 (&a0)[2], f32x16 (&a1)[2], bf16_t* stg, int cp,
;                          bf16_t*& rdst, int& rldd, int& rcoff, float rs0, float rs1) {
;     ...
;     float ss = 0.f;
; #pragma unroll
;     for (int i = 0; i < 16; ++i) { float t = a0[mt][i] * rs; v[0][i] = t; ss += t * t; }
; #pragma unroll
;     for (int i = 0; i < 16; ++i) { float t = a1[mt][i] * rs; v[1][i] = t; ss += t * t; }
;     if (type == NORM) {
;       ss += xor32(ss);
;       const float r = rsqrtf(ss * (1.f / 64.f) + 1e-6f) * scl;
; #pragma unroll
;       for (int nt = 0; nt < 2; ++nt)
; #pragma unroll
;         for (int qd = 0; qd < 4; ++qd) {
;           const int n = nt * 32 + 8 * qd + 4 * lh;
;           const float4 g4 = *(const float4*)(gain + n);
;           *(uint2*)(stg + (mt * 32 + lr) * 136 + cp * 64 + n) =
;               make_uint2(pack2(v[nt][4 * qd] * r * g4.x, v[nt][4 * qd + 1] * r * g4.y),
;                          pack2(v[nt][4 * qd + 2] * r * g4.z, v[nt][4 * qd + 3] * r * g4.w));
;         }
.LBB0_374:
	s_or_saveexec_b64 s[46:47], s[46:47]
	v_mul_u32_u24_e32 v104, 0x110, v158
	v_lshlrev_b32_e32 v105, 1, v155
	v_lshlrev_b32_e32 v192, 2, v155
	v_add3_u32 v110, v152, v104, v105
	s_xor_b64 exec, exec, s[46:47]
	s_cbranch_execz .LBB0_376
	v_pk_mul_f32 v[104:105], v[150:151], v[150:151]
	v_pk_mul_f32 v[106:107], v[148:149], v[148:149]
	v_add_f32_e32 v104, v104, v105
	v_add_f32_e32 v104, v106, v104
	v_pk_mul_f32 v[108:109], v[146:147], v[146:147]
	v_add_f32_e32 v104, v107, v104
	v_add_f32_e32 v104, v108, v104
	v_pk_mul_f32 v[124:125], v[144:145], v[144:145]
	v_add_f32_e32 v104, v109, v104
	v_add_f32_e32 v104, v124, v104
	v_and_b32_e32 v106, 64, v231
	v_pk_mul_f32 v[126:127], v[142:143], v[142:143]
	v_add_f32_e32 v104, v125, v104
	v_xor_b32_e32 v105, 32, v231
	v_add_u32_e32 v106, 64, v106
	v_add_f32_e32 v104, v126, v104
	v_cmp_lt_i32_e32 vcc, v105, v106
	v_lshl_add_u64 v[106:107], v[138:139], 0, v[192:193]
	v_add_f32_e32 v104, v127, v104
	global_load_dwordx4 v[124:127], v[106:107], off
	global_load_dwordx4 v[184:187], v[106:107], off offset:32
	global_load_dwordx4 v[188:191], v[106:107], off offset:64
	global_load_dwordx4 v[200:203], v[106:107], off offset:96
	global_load_dwordx4 v[204:207], v[106:107], off offset:128
	global_load_dwordx4 v[208:211], v[106:107], off offset:160
	global_load_dwordx4 v[212:215], v[106:107], off offset:192
	global_load_dwordx4 v[216:219], v[106:107], off offset:224
	v_pk_mul_f32 v[160:161], v[132:133], v[132:133]
	v_pk_mul_f32 v[162:163], v[122:123], v[122:123]
	v_add_f32_e32 v104, v160, v104
	v_add_f32_e32 v104, v161, v104
	v_add_f32_e32 v104, v162, v104
	v_pk_mul_f32 v[164:165], v[120:121], v[120:121]
	v_add_f32_e32 v104, v163, v104
	v_add_f32_e32 v104, v164, v104
	v_pk_mul_f32 v[166:167], v[118:119], v[118:119]
	v_add_f32_e32 v104, v165, v104
	v_add_f32_e32 v104, v166, v104
	v_pk_mul_f32 v[168:169], v[116:117], v[116:117]
	v_add_f32_e32 v104, v167, v104
	v_add_f32_e32 v104, v168, v104
	v_pk_mul_f32 v[170:171], v[114:115], v[114:115]
	v_add_f32_e32 v104, v169, v104
	v_add_f32_e32 v104, v170, v104
	v_pk_mul_f32 v[172:173], v[112:113], v[112:113]
	v_add_f32_e32 v104, v171, v104
	v_add_f32_e32 v104, v172, v104
	v_pk_mul_f32 v[174:175], v[98:99], v[98:99]
	v_add_f32_e32 v104, v173, v104
	v_add_f32_e32 v104, v174, v104
	v_pk_mul_f32 v[176:177], v[96:97], v[96:97]
	v_add_f32_e32 v104, v175, v104
	v_add_f32_e32 v104, v176, v104
	v_pk_mul_f32 v[178:179], v[102:103], v[102:103]
	v_add_f32_e32 v104, v177, v104
	v_add_f32_e32 v104, v178, v104
	v_pk_mul_f32 v[180:181], v[100:101], v[100:101]
	v_add_f32_e32 v104, v179, v104
	v_add_f32_e32 v104, v180, v104
	v_cndmask_b32_e32 v105, v231, v105, vcc
	v_add_f32_e32 v104, v181, v104
	v_lshlrev_b32_e32 v105, 2, v105
	ds_bpermute_b32 v105, v105, v104
	s_nop 0
	s_waitcnt lgkmcnt(0)
	v_add_f32_e32 v104, v104, v105
	v_fmamk_f32 v104, v104, 0x3c800000, v194
	v_cmp_gt_f32_e32 vcc, s23, v104
	v_mul_f32_e32 v105, 0x4b800000, v104
	s_nop 0
	v_cndmask_b32_e32 v104, v104, v105, vcc
	v_rsq_f32_e32 v104, v104
	s_nop 0
	v_mul_f32_e32 v105, 0x45800000, v104
	v_cndmask_b32_e32 v104, v104, v105, vcc
	v_mul_f32_e32 v104, v156, v104
	v_pk_mul_f32 v[108:109], v[150:151], v[104:105] op_sel_hi:[1,0]
	v_pk_mul_f32 v[146:147], v[146:147], v[104:105] op_sel_hi:[1,0]
	v_pk_mul_f32 v[144:145], v[144:145], v[104:105] op_sel_hi:[1,0]
	v_pk_mul_f32 v[122:123], v[122:123], v[104:105] op_sel_hi:[1,0]
	v_pk_mul_f32 v[120:121], v[120:121], v[104:105] op_sel_hi:[1,0]
	v_pk_mul_f32 v[116:117], v[116:117], v[104:105] op_sel_hi:[1,0]
	v_pk_mul_f32 v[114:115], v[114:115], v[104:105] op_sel_hi:[1,0]
	v_pk_mul_f32 v[112:113], v[112:113], v[104:105] op_sel_hi:[1,0]
	v_pk_mul_f32 v[98:99], v[98:99], v[104:105] op_sel_hi:[1,0]
	v_pk_mul_f32 v[96:97], v[96:97], v[104:105] op_sel_hi:[1,0]
	v_pk_mul_f32 v[102:103], v[102:103], v[104:105] op_sel_hi:[1,0]
	v_pk_mul_f32 v[100:101], v[100:101], v[104:105] op_sel_hi:[1,0]
	s_nop 0
	s_waitcnt vmcnt(7)
	v_pk_mul_f32 v[108:109], v[124:125], v[108:109]
	v_pk_mul_f32 v[124:125], v[148:149], v[104:105] op_sel_hi:[1,0]
	v_cvt_pk_bf16_f32 v108, v108, v109
	v_pk_mul_f32 v[124:125], v[126:127], v[124:125]
	s_nop 0
	v_cvt_pk_bf16_f32 v109, v124, v125
	s_nop 0
	s_nop 0
	s_waitcnt vmcnt(6)
	v_pk_mul_f32 v[124:125], v[184:185], v[146:147]
	v_pk_mul_f32 v[126:127], v[186:187], v[144:145]
	v_cvt_pk_bf16_f32 v124, v124, v125
	v_cvt_pk_bf16_f32 v125, v126, v127
	ds_write2_b64 v110, v[108:109], v[124:125] offset1:2
	s_nop 0
	v_pk_mul_f32 v[108:109], v[142:143], v[104:105] op_sel_hi:[1,0]
	s_nop 0
	s_waitcnt vmcnt(5)
	v_pk_mul_f32 v[108:109], v[108:109], v[188:189]
	v_pk_mul_f32 v[124:125], v[132:133], v[104:105] op_sel_hi:[1,0]
	v_cvt_pk_bf16_f32 v108, v108, v109
	v_pk_mul_f32 v[124:125], v[124:125], v[190:191]
	s_nop 0
	v_cvt_pk_bf16_f32 v109, v124, v125
	s_nop 0
	s_nop 0
	s_waitcnt vmcnt(4)
	v_pk_mul_f32 v[122:123], v[122:123], v[200:201]
	v_pk_mul_f32 v[120:121], v[120:121], v[202:203]
	v_cvt_pk_bf16_f32 v122, v122, v123
	v_cvt_pk_bf16_f32 v123, v120, v121
	ds_write2_b64 v110, v[108:109], v[122:123] offset0:4 offset1:6
	s_nop 0
	v_pk_mul_f32 v[108:109], v[118:119], v[104:105] op_sel_hi:[1,0]
	s_nop 0
	s_waitcnt vmcnt(3)
	v_pk_mul_f32 v[116:117], v[116:117], v[206:207]
	v_pk_mul_f32 v[108:109], v[108:109], v[204:205]
	s_nop 0
	v_cvt_pk_bf16_f32 v108, v108, v109
	v_cvt_pk_bf16_f32 v109, v116, v117
	s_nop 0
	s_nop 0
	s_waitcnt vmcnt(2)
	v_pk_mul_f32 v[114:115], v[114:115], v[208:209]
	v_pk_mul_f32 v[112:113], v[112:113], v[210:211]
	v_cvt_pk_bf16_f32 v114, v114, v115
	v_cvt_pk_bf16_f32 v115, v112, v113
	ds_write2_b64 v110, v[108:109], v[114:115] offset0:8 offset1:10
	s_nop 0
	s_nop 0
	s_waitcnt vmcnt(1)
	v_pk_mul_f32 v[98:99], v[98:99], v[212:213]
	v_pk_mul_f32 v[96:97], v[96:97], v[214:215]
	v_cvt_pk_bf16_f32 v108, v98, v99
	v_cvt_pk_bf16_f32 v109, v96, v97
	s_nop 0
	s_nop 0
	s_waitcnt vmcnt(0)
	v_pk_mul_f32 v[96:97], v[102:103], v[216:217]
	v_pk_mul_f32 v[98:99], v[100:101], v[218:219]
	v_cvt_pk_bf16_f32 v96, v96, v97
	v_cvt_pk_bf16_f32 v97, v98, v99
	ds_write2_b64 v110, v[108:109], v[96:97] offset0:12 offset1:14

; DI unsigned pack2(float a, float b) { f32x2_t v = {a, b}; bf16x2_t r = __builtin_convertvector(v, bf16x2_t); return __builtin_bit_cast(unsigned, r); }
; DI float xor32(float v) { return __shfl_xor(v, 32); }
; DI bool epi_inproj_chunk(const P& p, int layer, int ch, int m0w, f32x16 (&a0)[2], f32x16 (&a1)[2], bf16_t* stg, int cp,
;                          bf16_t*& rdst, int& rldd, int& rcoff, float rs0, float rs1) {
;     ...
;     float ss = 0.f;
; #pragma unroll
;     for (int i = 0; i < 16; ++i) { float t = a0[mt][i] * rs; v[0][i] = t; ss += t * t; }
; #pragma unroll
;     for (int i = 0; i < 16; ++i) { float t = a1[mt][i] * rs; v[1][i] = t; ss += t * t; }
;     if (type == NORM) {
;       ss += xor32(ss);
;       const float r = rsqrtf(ss * (1.f / 64.f) + 1e-6f) * scl;
; #pragma unroll
;       for (int nt = 0; nt < 2; ++nt)
; #pragma unroll
;         for (int qd = 0; qd < 4; ++qd) {
;           const int n = nt * 32 + 8 * qd + 4 * lh;
;           const float4 g4 = *(const float4*)(gain + n);
;           *(uint2*)(stg + (mt * 32 + lr) * 136 + cp * 64 + n) =
;               make_uint2(pack2(v[nt][4 * qd] * r * g4.x, v[nt][4 * qd + 1] * r * g4.y),
;                          pack2(v[nt][4 * qd + 2] * r * g4.z, v[nt][4 * qd + 3] * r * g4.w));
;         }
.LBB0_422:
	s_andn2_saveexec_b64 s[0:1], s[44:45]
	s_cbranch_execz .LBB0_424
	v_pk_mul_f32 v[72:73], v[106:107], v[106:107]
	v_pk_mul_f32 v[74:75], v[104:105], v[104:105]
	v_add_f32_e32 v72, v72, v73
	v_add_f32_e32 v72, v74, v72
	v_pk_mul_f32 v[76:77], v[102:103], v[102:103]
	v_add_f32_e32 v72, v75, v72
	v_add_f32_e32 v72, v76, v72
	v_and_b32_e32 v74, 64, v231
	v_pk_mul_f32 v[78:79], v[100:101], v[100:101]
	v_add_f32_e32 v72, v77, v72
	v_xor_b32_e32 v73, 32, v231
	v_add_u32_e32 v74, 64, v74
	v_add_f32_e32 v72, v78, v72
	v_cmp_lt_i32_e32 vcc, v73, v74
	v_lshl_add_u64 v[74:75], v[138:139], 0, v[192:193]
	v_add_f32_e32 v72, v79, v72
	global_load_dwordx4 v[76:79], v[74:75], off
	global_load_dwordx4 v[184:187], v[74:75], off offset:32
	global_load_dwordx4 v[188:191], v[74:75], off offset:64
	global_load_dwordx4 v[200:203], v[74:75], off offset:96
	global_load_dwordx4 v[204:207], v[74:75], off offset:128
	global_load_dwordx4 v[208:211], v[74:75], off offset:160
	global_load_dwordx4 v[212:215], v[74:75], off offset:192
	global_load_dwordx4 v[216:219], v[74:75], off offset:224
	v_pk_mul_f32 v[92:93], v[98:99], v[98:99]
	v_pk_mul_f32 v[94:95], v[96:97], v[96:97]
	v_add_f32_e32 v72, v92, v72
	v_add_f32_e32 v72, v93, v72
	v_add_f32_e32 v72, v94, v72
	v_pk_mul_f32 v[108:109], v[90:91], v[90:91]
	v_add_f32_e32 v72, v95, v72
	v_add_f32_e32 v72, v108, v72
	v_pk_mul_f32 v[112:113], v[88:89], v[88:89]
	v_add_f32_e32 v72, v109, v72
	v_add_f32_e32 v72, v112, v72
	v_pk_mul_f32 v[114:115], v[86:87], v[86:87]
	v_add_f32_e32 v72, v113, v72
	v_add_f32_e32 v72, v114, v72
	v_pk_mul_f32 v[116:117], v[84:85], v[84:85]
	v_add_f32_e32 v72, v115, v72
	v_add_f32_e32 v72, v116, v72
	v_pk_mul_f32 v[118:119], v[82:83], v[82:83]
	v_add_f32_e32 v72, v117, v72
	v_add_f32_e32 v72, v118, v72
	v_pk_mul_f32 v[120:121], v[80:81], v[80:81]
	v_add_f32_e32 v72, v119, v72
	v_add_f32_e32 v72, v120, v72
	v_pk_mul_f32 v[122:123], v[66:67], v[66:67]
	v_add_f32_e32 v72, v121, v72
	v_add_f32_e32 v72, v122, v72
	v_pk_mul_f32 v[124:125], v[64:65], v[64:65]
	v_add_f32_e32 v72, v123, v72
	v_add_f32_e32 v72, v124, v72
	v_pk_mul_f32 v[126:127], v[70:71], v[70:71]
	v_add_f32_e32 v72, v125, v72
	v_add_f32_e32 v72, v126, v72
	v_pk_mul_f32 v[130:131], v[68:69], v[68:69]
	v_add_f32_e32 v72, v127, v72
	v_add_f32_e32 v72, v130, v72
	v_cndmask_b32_e32 v73, v231, v73, vcc
	v_add_f32_e32 v72, v131, v72
	v_lshlrev_b32_e32 v73, 2, v73
	ds_bpermute_b32 v73, v73, v72
	s_nop 0
	s_waitcnt lgkmcnt(0)
	v_add_f32_e32 v72, v72, v73
	v_fmamk_f32 v72, v72, 0x3c800000, v194
	v_cmp_gt_f32_e32 vcc, s23, v72
	v_mul_f32_e32 v73, 0x4b800000, v72
	s_nop 0
	v_cndmask_b32_e32 v72, v72, v73, vcc
	v_rsq_f32_e32 v72, v72
	s_nop 0
	v_mul_f32_e32 v73, 0x45800000, v72
	v_cndmask_b32_e32 v72, v72, v73, vcc
	v_mul_f32_e32 v72, v156, v72
	v_pk_mul_f32 v[92:93], v[106:107], v[72:73] op_sel_hi:[1,0]
	v_pk_mul_f32 v[94:95], v[102:103], v[72:73] op_sel_hi:[1,0]
	s_nop 0
	s_waitcnt vmcnt(7)
	v_pk_mul_f32 v[76:77], v[76:77], v[92:93]
	s_nop 0
	v_cvt_pk_bf16_f32 v92, v76, v77
	v_pk_mul_f32 v[76:77], v[104:105], v[72:73] op_sel_hi:[1,0]
	s_nop 0
	v_pk_mul_f32 v[76:77], v[78:79], v[76:77]
	s_nop 0
	v_cvt_pk_bf16_f32 v93, v76, v77
	s_nop 0
	s_nop 0
	s_waitcnt vmcnt(6)
	v_pk_mul_f32 v[76:77], v[184:185], v[94:95]
	v_pk_mul_f32 v[94:95], v[100:101], v[72:73] op_sel_hi:[1,0]
	v_cvt_pk_bf16_f32 v76, v76, v77
	v_pk_mul_f32 v[78:79], v[186:187], v[94:95]
	v_add_u32_e32 v73, 0x2000, v110
	v_cvt_pk_bf16_f32 v77, v78, v79
	ds_write2_b64 v73, v[92:93], v[76:77] offset0:64 offset1:66
	s_nop 0
	v_pk_mul_f32 v[92:93], v[98:99], v[72:73] op_sel_hi:[1,0]
	v_pk_mul_f32 v[90:91], v[90:91], v[72:73] op_sel_hi:[1,0]
	v_pk_mul_f32 v[88:89], v[88:89], v[72:73] op_sel_hi:[1,0]
	v_pk_mul_f32 v[86:87], v[86:87], v[72:73] op_sel_hi:[1,0]
	v_pk_mul_f32 v[82:83], v[82:83], v[72:73] op_sel_hi:[1,0]
	v_pk_mul_f32 v[80:81], v[80:81], v[72:73] op_sel_hi:[1,0]
	v_pk_mul_f32 v[66:67], v[66:67], v[72:73] op_sel_hi:[1,0]
	v_pk_mul_f32 v[64:65], v[64:65], v[72:73] op_sel_hi:[1,0]
	v_pk_mul_f32 v[70:71], v[70:71], v[72:73] op_sel_hi:[1,0]
	v_pk_mul_f32 v[68:69], v[68:69], v[72:73] op_sel_hi:[1,0]
	s_nop 0
	s_waitcnt vmcnt(5)
	v_pk_mul_f32 v[76:77], v[92:93], v[188:189]
	s_nop 0
	v_cvt_pk_bf16_f32 v92, v76, v77
	v_pk_mul_f32 v[76:77], v[96:97], v[72:73] op_sel_hi:[1,0]
	s_nop 0
	v_pk_mul_f32 v[76:77], v[76:77], v[190:191]
	s_nop 0
	v_cvt_pk_bf16_f32 v93, v76, v77
	s_nop 0
	s_nop 0
	s_waitcnt vmcnt(4)
	v_pk_mul_f32 v[76:77], v[90:91], v[200:201]
	v_pk_mul_f32 v[78:79], v[88:89], v[202:203]
	v_cvt_pk_bf16_f32 v76, v76, v77
	v_cvt_pk_bf16_f32 v77, v78, v79
	ds_write2_b64 v73, v[92:93], v[76:77] offset0:68 offset1:70
	s_nop 0
	s_nop 0
	s_waitcnt vmcnt(3)
	v_pk_mul_f32 v[76:77], v[86:87], v[204:205]
	s_nop 0
	v_cvt_pk_bf16_f32 v86, v76, v77
	v_pk_mul_f32 v[76:77], v[84:85], v[72:73] op_sel_hi:[1,0]
	s_nop 0
	v_pk_mul_f32 v[76:77], v[76:77], v[206:207]
	s_nop 0
	v_cvt_pk_bf16_f32 v87, v76, v77
	s_nop 0
	s_nop 0
	s_waitcnt vmcnt(2)
	v_pk_mul_f32 v[76:77], v[82:83], v[208:209]
	v_pk_mul_f32 v[78:79], v[80:81], v[210:211]
	v_cvt_pk_bf16_f32 v76, v76, v77
	v_cvt_pk_bf16_f32 v77, v78, v79
	ds_write2_b64 v73, v[86:87], v[76:77] offset0:72 offset1:74
	s_nop 0
	s_nop 0
	s_waitcnt vmcnt(1)
	v_pk_mul_f32 v[66:67], v[66:67], v[212:213]
	v_pk_mul_f32 v[64:65], v[64:65], v[214:215]
	v_cvt_pk_bf16_f32 v76, v66, v67
	v_cvt_pk_bf16_f32 v77, v64, v65
	s_nop 0
	s_nop 0
	s_waitcnt vmcnt(0)
	v_pk_mul_f32 v[64:65], v[70:71], v[216:217]
	v_pk_mul_f32 v[66:67], v[68:69], v[218:219]
	v_cvt_pk_bf16_f32 v64, v64, v65
	v_cvt_pk_bf16_f32 v65, v66, v67
	ds_write2_b64 v73, v[76:77], v[64:65] offset0:76 offset1:78

; DI unsigned pack2(float a, float b) { f32x2_t v = {a, b}; bf16x2_t r = __builtin_convertvector(v, bf16x2_t); return __builtin_bit_cast(unsigned, r); }
; DI float xor32(float v) { return __shfl_xor(v, 32); }
; DI bool epi_inproj_chunk(const P& p, int layer, int ch, int m0w, f32x16 (&a0)[2], f32x16 (&a1)[2], bf16_t* stg, int cp,
;                          bf16_t*& rdst, int& rldd, int& rcoff, float rs0, float rs1) {
;     ...
;     float ss = 0.f;
; #pragma unroll
;     for (int i = 0; i < 16; ++i) { float t = a0[mt][i] * rs; v[0][i] = t; ss += t * t; }
; #pragma unroll
;     for (int i = 0; i < 16; ++i) { float t = a1[mt][i] * rs; v[1][i] = t; ss += t * t; }
;     if (type == NORM) {
;       ss += xor32(ss);
;       const float r = rsqrtf(ss * (1.f / 64.f) + 1e-6f) * scl;
; #pragma unroll
;       for (int nt = 0; nt < 2; ++nt)
; #pragma unroll
;         for (int qd = 0; qd < 4; ++qd) {
;           const int n = nt * 32 + 8 * qd + 4 * lh;
;           const float4 g4 = *(const float4*)(gain + n);
;           *(uint2*)(stg + (mt * 32 + lr) * 136 + cp * 64 + n) =
;               make_uint2(pack2(v[nt][4 * qd] * r * g4.x, v[nt][4 * qd + 1] * r * g4.y),
;                          pack2(v[nt][4 * qd + 2] * r * g4.z, v[nt][4 * qd + 3] * r * g4.w));
;         }
.LBB0_520:
	s_or_saveexec_b64 s[50:51], s[50:51]
	v_mul_u32_u24_e32 v40, 0x110, v91
	v_lshlrev_b32_e32 v41, 1, v88
	v_lshlrev_b32_e32 v192, 2, v88
	v_add3_u32 v46, v152, v40, v41
	s_xor_b64 exec, exec, s[50:51]
	s_cbranch_execz .LBB0_522
	v_pk_mul_f32 v[40:41], v[84:85], v[84:85]
	v_pk_mul_f32 v[42:43], v[82:83], v[82:83]
	v_add_f32_e32 v40, v40, v41
	v_add_f32_e32 v40, v42, v40
	v_pk_mul_f32 v[44:45], v[80:81], v[80:81]
	v_add_f32_e32 v40, v43, v40
	v_add_f32_e32 v40, v44, v40
	v_pk_mul_f32 v[60:61], v[78:79], v[78:79]
	v_add_f32_e32 v40, v45, v40
	v_add_f32_e32 v40, v60, v40
	v_and_b32_e32 v42, 64, v231
	v_pk_mul_f32 v[62:63], v[76:77], v[76:77]
	v_add_f32_e32 v40, v61, v40
	v_xor_b32_e32 v41, 32, v231
	v_add_u32_e32 v42, 64, v42
	v_add_f32_e32 v40, v62, v40
	v_cmp_lt_i32_e32 vcc, v41, v42
	v_lshl_add_u64 v[42:43], v[64:65], 0, v[192:193]
	v_add_f32_e32 v40, v63, v40
	global_load_dwordx4 v[60:63], v[42:43], off
	global_load_dwordx4 v[184:187], v[42:43], off offset:32
	global_load_dwordx4 v[188:191], v[42:43], off offset:64
	global_load_dwordx4 v[200:203], v[42:43], off offset:96
	global_load_dwordx4 v[204:207], v[42:43], off offset:128
	global_load_dwordx4 v[208:211], v[42:43], off offset:160
	global_load_dwordx4 v[212:215], v[42:43], off offset:192
	global_load_dwordx4 v[216:219], v[42:43], off offset:224
	v_pk_mul_f32 v[92:93], v[74:75], v[74:75]
	v_pk_mul_f32 v[94:95], v[58:59], v[58:59]
	v_add_f32_e32 v40, v92, v40
	v_add_f32_e32 v40, v93, v40
	v_add_f32_e32 v40, v94, v40
	v_pk_mul_f32 v[96:97], v[56:57], v[56:57]
	v_add_f32_e32 v40, v95, v40
	v_add_f32_e32 v40, v96, v40
	v_pk_mul_f32 v[98:99], v[54:55], v[54:55]
	v_add_f32_e32 v40, v97, v40
	v_add_f32_e32 v40, v98, v40
	v_pk_mul_f32 v[100:101], v[52:53], v[52:53]
	v_add_f32_e32 v40, v99, v40
	v_add_f32_e32 v40, v100, v40
	v_pk_mul_f32 v[102:103], v[50:51], v[50:51]
	v_add_f32_e32 v40, v101, v40
	v_add_f32_e32 v40, v102, v40
	v_pk_mul_f32 v[104:105], v[48:49], v[48:49]
	v_add_f32_e32 v40, v103, v40
	v_add_f32_e32 v40, v104, v40
	v_pk_mul_f32 v[106:107], v[34:35], v[34:35]
	v_add_f32_e32 v40, v105, v40
	v_add_f32_e32 v40, v106, v40
	v_pk_mul_f32 v[108:109], v[32:33], v[32:33]
	v_add_f32_e32 v40, v107, v40
	v_add_f32_e32 v40, v108, v40
	v_pk_mul_f32 v[110:111], v[38:39], v[38:39]
	v_add_f32_e32 v40, v109, v40
	v_add_f32_e32 v40, v110, v40
	v_pk_mul_f32 v[112:113], v[36:37], v[36:37]
	v_add_f32_e32 v40, v111, v40
	v_add_f32_e32 v40, v112, v40
	v_cndmask_b32_e32 v41, v231, v41, vcc
	v_add_f32_e32 v40, v113, v40
	v_lshlrev_b32_e32 v41, 2, v41
	ds_bpermute_b32 v41, v41, v40
	s_nop 0
	s_waitcnt lgkmcnt(0)
	v_add_f32_e32 v40, v40, v41
	v_fmamk_f32 v40, v40, 0x3c800000, v194
	v_cmp_gt_f32_e32 vcc, s23, v40
	v_mul_f32_e32 v41, 0x4b800000, v40
	s_nop 0
	v_cndmask_b32_e32 v40, v40, v41, vcc
	v_rsq_f32_e32 v40, v40
	s_nop 0
	v_mul_f32_e32 v41, 0x45800000, v40
	v_cndmask_b32_e32 v40, v40, v41, vcc
	v_mul_f32_e32 v40, v89, v40
	v_pk_mul_f32 v[44:45], v[84:85], v[40:41] op_sel_hi:[1,0]
	v_pk_mul_f32 v[80:81], v[80:81], v[40:41] op_sel_hi:[1,0]
	v_pk_mul_f32 v[78:79], v[78:79], v[40:41] op_sel_hi:[1,0]
	v_pk_mul_f32 v[58:59], v[58:59], v[40:41] op_sel_hi:[1,0]
	v_pk_mul_f32 v[56:57], v[56:57], v[40:41] op_sel_hi:[1,0]
	v_pk_mul_f32 v[52:53], v[52:53], v[40:41] op_sel_hi:[1,0]
	v_pk_mul_f32 v[50:51], v[50:51], v[40:41] op_sel_hi:[1,0]
	v_pk_mul_f32 v[48:49], v[48:49], v[40:41] op_sel_hi:[1,0]
	v_pk_mul_f32 v[34:35], v[34:35], v[40:41] op_sel_hi:[1,0]
	v_pk_mul_f32 v[32:33], v[32:33], v[40:41] op_sel_hi:[1,0]
	v_pk_mul_f32 v[38:39], v[38:39], v[40:41] op_sel_hi:[1,0]
	v_pk_mul_f32 v[36:37], v[36:37], v[40:41] op_sel_hi:[1,0]
	s_nop 0
	s_waitcnt vmcnt(7)
	v_pk_mul_f32 v[44:45], v[60:61], v[44:45]
	v_pk_mul_f32 v[60:61], v[82:83], v[40:41] op_sel_hi:[1,0]
	v_cvt_pk_bf16_f32 v44, v44, v45
	v_pk_mul_f32 v[60:61], v[62:63], v[60:61]
	s_nop 0
	v_cvt_pk_bf16_f32 v45, v60, v61
	s_nop 0
	s_nop 0
	s_waitcnt vmcnt(6)
	v_pk_mul_f32 v[60:61], v[184:185], v[80:81]
	v_pk_mul_f32 v[62:63], v[186:187], v[78:79]
	v_cvt_pk_bf16_f32 v60, v60, v61
	v_cvt_pk_bf16_f32 v61, v62, v63
	ds_write2_b64 v46, v[44:45], v[60:61] offset0:16 offset1:18
	s_nop 0
	v_pk_mul_f32 v[44:45], v[76:77], v[40:41] op_sel_hi:[1,0]
	s_nop 0
	s_waitcnt vmcnt(5)
	v_pk_mul_f32 v[44:45], v[44:45], v[188:189]
	v_pk_mul_f32 v[60:61], v[74:75], v[40:41] op_sel_hi:[1,0]
	v_cvt_pk_bf16_f32 v44, v44, v45
	v_pk_mul_f32 v[60:61], v[60:61], v[190:191]
	s_nop 0
	v_cvt_pk_bf16_f32 v45, v60, v61
	s_nop 0
	s_nop 0
	s_waitcnt vmcnt(4)
	v_pk_mul_f32 v[58:59], v[58:59], v[200:201]
	v_pk_mul_f32 v[56:57], v[56:57], v[202:203]
	v_cvt_pk_bf16_f32 v58, v58, v59
	v_cvt_pk_bf16_f32 v59, v56, v57
	ds_write2_b64 v46, v[44:45], v[58:59] offset0:20 offset1:22
	s_nop 0
	v_pk_mul_f32 v[44:45], v[54:55], v[40:41] op_sel_hi:[1,0]
	s_nop 0
	s_waitcnt vmcnt(3)
	v_pk_mul_f32 v[52:53], v[52:53], v[206:207]
	v_pk_mul_f32 v[44:45], v[44:45], v[204:205]
	s_nop 0
	v_cvt_pk_bf16_f32 v44, v44, v45
	v_cvt_pk_bf16_f32 v45, v52, v53
	s_nop 0
	s_nop 0
	s_waitcnt vmcnt(2)
	v_pk_mul_f32 v[50:51], v[50:51], v[208:209]
	v_pk_mul_f32 v[48:49], v[48:49], v[210:211]
	v_cvt_pk_bf16_f32 v50, v50, v51
	v_cvt_pk_bf16_f32 v51, v48, v49
	ds_write2_b64 v46, v[44:45], v[50:51] offset0:24 offset1:26
	s_nop 0
	s_nop 0
	s_waitcnt vmcnt(1)
	v_pk_mul_f32 v[34:35], v[34:35], v[212:213]
	v_pk_mul_f32 v[32:33], v[32:33], v[214:215]
	v_cvt_pk_bf16_f32 v44, v34, v35
	v_cvt_pk_bf16_f32 v45, v32, v33
	s_nop 0
	s_nop 0
	s_waitcnt vmcnt(0)
	v_pk_mul_f32 v[32:33], v[38:39], v[216:217]
	v_pk_mul_f32 v[34:35], v[36:37], v[218:219]
	v_cvt_pk_bf16_f32 v32, v32, v33
	v_cvt_pk_bf16_f32 v33, v34, v35
	ds_write2_b64 v46, v[44:45], v[32:33] offset0:28 offset1:30

; DI unsigned pack2(float a, float b) { f32x2_t v = {a, b}; bf16x2_t r = __builtin_convertvector(v, bf16x2_t); return __builtin_bit_cast(unsigned, r); }
; DI float xor32(float v) { return __shfl_xor(v, 32); }
; DI bool epi_inproj_chunk(const P& p, int layer, int ch, int m0w, f32x16 (&a0)[2], f32x16 (&a1)[2], bf16_t* stg, int cp,
;                          bf16_t*& rdst, int& rldd, int& rcoff, float rs0, float rs1) {
;     ...
;     float ss = 0.f;
; #pragma unroll
;     for (int i = 0; i < 16; ++i) { float t = a0[mt][i] * rs; v[0][i] = t; ss += t * t; }
; #pragma unroll
;     for (int i = 0; i < 16; ++i) { float t = a1[mt][i] * rs; v[1][i] = t; ss += t * t; }
;     if (type == NORM) {
;       ss += xor32(ss);
;       const float r = rsqrtf(ss * (1.f / 64.f) + 1e-6f) * scl;
; #pragma unroll
;       for (int nt = 0; nt < 2; ++nt)
; #pragma unroll
;         for (int qd = 0; qd < 4; ++qd) {
;           const int n = nt * 32 + 8 * qd + 4 * lh;
;           const float4 g4 = *(const float4*)(gain + n);
;           *(uint2*)(stg + (mt * 32 + lr) * 136 + cp * 64 + n) =
;               make_uint2(pack2(v[nt][4 * qd] * r * g4.x, v[nt][4 * qd + 1] * r * g4.y),
;                          pack2(v[nt][4 * qd + 2] * r * g4.z, v[nt][4 * qd + 3] * r * g4.w));
;         }
.LBB0_568:
	s_andn2_saveexec_b64 s[30:31], s[46:47]
	s_cbranch_execz .LBB0_570
	v_pk_mul_f32 v[8:9], v[42:43], v[42:43]
	v_pk_mul_f32 v[10:11], v[40:41], v[40:41]
	v_add_f32_e32 v8, v8, v9
	v_add_f32_e32 v8, v10, v8
	v_pk_mul_f32 v[12:13], v[38:39], v[38:39]
	v_add_f32_e32 v8, v11, v8
	v_add_f32_e32 v8, v12, v8
	v_and_b32_e32 v10, 64, v231
	v_pk_mul_f32 v[14:15], v[36:37], v[36:37]
	v_add_f32_e32 v8, v13, v8
	v_xor_b32_e32 v9, 32, v231
	v_add_u32_e32 v10, 64, v10
	v_add_f32_e32 v8, v14, v8
	v_cmp_lt_i32_e32 vcc, v9, v10
	v_lshl_add_u64 v[10:11], v[64:65], 0, v[192:193]
	v_add_f32_e32 v8, v15, v8
	global_load_dwordx4 v[12:15], v[10:11], off
	global_load_dwordx4 v[184:187], v[10:11], off offset:32
	global_load_dwordx4 v[188:191], v[10:11], off offset:64
	global_load_dwordx4 v[200:203], v[10:11], off offset:96
	global_load_dwordx4 v[204:207], v[10:11], off offset:128
	global_load_dwordx4 v[208:211], v[10:11], off offset:160
	global_load_dwordx4 v[212:215], v[10:11], off offset:192
	global_load_dwordx4 v[216:219], v[10:11], off offset:224
	v_pk_mul_f32 v[28:29], v[34:35], v[34:35]
	v_pk_mul_f32 v[30:31], v[32:33], v[32:33]
	v_add_f32_e32 v8, v28, v8
	v_add_f32_e32 v8, v29, v8
	v_add_f32_e32 v8, v30, v8
	v_pk_mul_f32 v[44:45], v[26:27], v[26:27]
	v_add_f32_e32 v8, v31, v8
	v_add_f32_e32 v8, v44, v8
	v_pk_mul_f32 v[48:49], v[24:25], v[24:25]
	v_add_f32_e32 v8, v45, v8
	v_add_f32_e32 v8, v48, v8
	v_pk_mul_f32 v[50:51], v[22:23], v[22:23]
	v_add_f32_e32 v8, v49, v8
	v_add_f32_e32 v8, v50, v8
	v_pk_mul_f32 v[52:53], v[20:21], v[20:21]
	v_add_f32_e32 v8, v51, v8
	v_add_f32_e32 v8, v52, v8
	v_pk_mul_f32 v[54:55], v[18:19], v[18:19]
	v_add_f32_e32 v8, v53, v8
	v_add_f32_e32 v8, v54, v8
	v_pk_mul_f32 v[56:57], v[16:17], v[16:17]
	v_add_f32_e32 v8, v55, v8
	v_add_f32_e32 v8, v56, v8
	v_pk_mul_f32 v[58:59], v[2:3], v[2:3]
	v_add_f32_e32 v8, v57, v8
	v_add_f32_e32 v8, v58, v8
	v_pk_mul_f32 v[60:61], v[0:1], v[0:1]
	v_add_f32_e32 v8, v59, v8
	v_add_f32_e32 v8, v60, v8
	v_pk_mul_f32 v[62:63], v[6:7], v[6:7]
	v_add_f32_e32 v8, v61, v8
	v_add_f32_e32 v8, v62, v8
	v_pk_mul_f32 v[66:67], v[4:5], v[4:5]
	v_add_f32_e32 v8, v63, v8
	v_add_f32_e32 v8, v66, v8
	v_cndmask_b32_e32 v9, v231, v9, vcc
	v_add_f32_e32 v8, v67, v8
	v_lshlrev_b32_e32 v9, 2, v9
	ds_bpermute_b32 v9, v9, v8
	s_nop 0
	s_waitcnt lgkmcnt(0)
	v_add_f32_e32 v8, v8, v9
	v_fmamk_f32 v8, v8, 0x3c800000, v194
	v_cmp_gt_f32_e32 vcc, s23, v8
	v_mul_f32_e32 v9, 0x4b800000, v8
	s_nop 0
	v_cndmask_b32_e32 v8, v8, v9, vcc
	v_rsq_f32_e32 v8, v8
	s_nop 0
	v_mul_f32_e32 v9, 0x45800000, v8
	v_cndmask_b32_e32 v8, v8, v9, vcc
	v_mul_f32_e32 v8, v89, v8
	v_pk_mul_f32 v[28:29], v[42:43], v[8:9] op_sel_hi:[1,0]
	v_pk_mul_f32 v[30:31], v[38:39], v[8:9] op_sel_hi:[1,0]
	s_nop 0
	s_waitcnt vmcnt(7)
	v_pk_mul_f32 v[12:13], v[12:13], v[28:29]
	s_nop 0
	v_cvt_pk_bf16_f32 v28, v12, v13
	v_pk_mul_f32 v[12:13], v[40:41], v[8:9] op_sel_hi:[1,0]
	s_nop 0
	v_pk_mul_f32 v[12:13], v[14:15], v[12:13]
	s_nop 0
	v_cvt_pk_bf16_f32 v29, v12, v13
	s_nop 0
	s_nop 0
	s_waitcnt vmcnt(6)
	v_pk_mul_f32 v[12:13], v[184:185], v[30:31]
	v_pk_mul_f32 v[30:31], v[36:37], v[8:9] op_sel_hi:[1,0]
	v_cvt_pk_bf16_f32 v12, v12, v13
	v_pk_mul_f32 v[14:15], v[186:187], v[30:31]
	v_add_u32_e32 v9, 0x2000, v46
	v_cvt_pk_bf16_f32 v13, v14, v15
	ds_write2_b64 v9, v[28:29], v[12:13] offset0:80 offset1:82
	s_nop 0
	v_pk_mul_f32 v[28:29], v[34:35], v[8:9] op_sel_hi:[1,0]
	v_pk_mul_f32 v[26:27], v[26:27], v[8:9] op_sel_hi:[1,0]
	v_pk_mul_f32 v[24:25], v[24:25], v[8:9] op_sel_hi:[1,0]
	v_pk_mul_f32 v[22:23], v[22:23], v[8:9] op_sel_hi:[1,0]
	v_pk_mul_f32 v[18:19], v[18:19], v[8:9] op_sel_hi:[1,0]
	v_pk_mul_f32 v[16:17], v[16:17], v[8:9] op_sel_hi:[1,0]
	v_pk_mul_f32 v[2:3], v[2:3], v[8:9] op_sel_hi:[1,0]
	v_pk_mul_f32 v[0:1], v[0:1], v[8:9] op_sel_hi:[1,0]
	v_pk_mul_f32 v[6:7], v[6:7], v[8:9] op_sel_hi:[1,0]
	v_pk_mul_f32 v[4:5], v[4:5], v[8:9] op_sel_hi:[1,0]
	s_nop 0
	s_waitcnt vmcnt(5)
	v_pk_mul_f32 v[12:13], v[28:29], v[188:189]
	s_nop 0
	v_cvt_pk_bf16_f32 v28, v12, v13
	v_pk_mul_f32 v[12:13], v[32:33], v[8:9] op_sel_hi:[1,0]
	s_nop 0
	v_pk_mul_f32 v[12:13], v[12:13], v[190:191]
	s_nop 0
	v_cvt_pk_bf16_f32 v29, v12, v13
	s_nop 0
	s_nop 0
	s_waitcnt vmcnt(4)
	v_pk_mul_f32 v[12:13], v[26:27], v[200:201]
	v_pk_mul_f32 v[14:15], v[24:25], v[202:203]
	v_cvt_pk_bf16_f32 v12, v12, v13
	v_cvt_pk_bf16_f32 v13, v14, v15
	ds_write2_b64 v9, v[28:29], v[12:13] offset0:84 offset1:86
	s_nop 0
	s_nop 0
	s_waitcnt vmcnt(3)
	v_pk_mul_f32 v[12:13], v[22:23], v[204:205]
	s_nop 0
	v_cvt_pk_bf16_f32 v22, v12, v13
	v_pk_mul_f32 v[12:13], v[20:21], v[8:9] op_sel_hi:[1,0]
	s_nop 0
	v_pk_mul_f32 v[12:13], v[12:13], v[206:207]
	s_nop 0
	v_cvt_pk_bf16_f32 v23, v12, v13
	s_nop 0
	s_nop 0
	s_waitcnt vmcnt(2)
	v_pk_mul_f32 v[12:13], v[18:19], v[208:209]
	v_pk_mul_f32 v[14:15], v[16:17], v[210:211]
	v_cvt_pk_bf16_f32 v12, v12, v13
	v_cvt_pk_bf16_f32 v13, v14, v15
	ds_write2_b64 v9, v[22:23], v[12:13] offset0:88 offset1:90
	s_nop 0
	s_nop 0
	s_waitcnt vmcnt(1)
	v_pk_mul_f32 v[2:3], v[2:3], v[212:213]
	v_pk_mul_f32 v[0:1], v[0:1], v[214:215]
	v_cvt_pk_bf16_f32 v12, v2, v3
	v_cvt_pk_bf16_f32 v13, v0, v1
	s_nop 0
	s_nop 0
	s_waitcnt vmcnt(0)
	v_pk_mul_f32 v[0:1], v[6:7], v[216:217]
	v_pk_mul_f32 v[2:3], v[4:5], v[218:219]
	v_cvt_pk_bf16_f32 v0, v0, v1
	v_cvt_pk_bf16_f32 v1, v2, v3
	ds_write2_b64 v9, v[12:13], v[0:1] offset0:92 offset1:94

; DI float xor32(float v) { return __shfl_xor(v, 32); }
; DI void phase_resid(const P& p, const bf16_t* W, const bf16_t* X, int K, bf16_t* sm, const Geo& ge, bool last) {
;     ...
;     for (int cp = 0; cp < 2; ++cp) {
; #pragma unroll 4
;       for (int it = 0; it < 8; ++it) {
;         const int row = it * 8 + (lane >> 3), c8 = (lane & 7) * 8;
;         const u32x4 raw = *(const u32x4*)(xb + (size_t)(m0w + row) * LDK1 + n0w + cp * 64 + c8);
;         float* d = stg + row * 68 + c8;
;         *(float4*)(d) = make_float4(__uint_as_float(raw[0] << 16), __uint_as_float(raw[0] & 0xffff0000u),
;                                     __uint_as_float(raw[1] << 16), __uint_as_float(raw[1] & 0xffff0000u));
;         *(float4*)(d + 4) = make_float4(__uint_as_float(raw[2] << 16), __uint_as_float(raw[2] & 0xffff0000u),
;                                         __uint_as_float(raw[3] << 16), __uint_as_float(raw[3] & 0xffff0000u));
;       }
; #pragma unroll
;       for (int mt = 0; mt < 2; ++mt) {
;         float ss = 0.f;
; #pragma unroll
;         for (int nh = 0; nh < 2; ++nh)
; #pragma unroll
;           for (int qd = 0; qd < 4; ++qd) {
;             const int nt = cp * 2 + nh;
;             float4* sp = (float4*)(stg + (mt * 32 + lr) * 68 + nh * 32 + 8 * qd + 4 * lh);
;             float4 v = *sp;
;             v.x += acc[nt][mt][4 * qd]; v.y += acc[nt][mt][4 * qd + 1]; v.z += acc[nt][mt][4 * qd + 2]; v.w += acc[nt][mt][4 * qd + 3];
;             *sp = v;
;             ss += v.x * v.x + v.y * v.y + v.z * v.z + v.w * v.w;
;           }
;         ss += xor32(ss);
;         if (lh == 0) part[(size_t)(m0w + mt * 32 + lr) * 16 + nt_ * 4 + wn * 2 + cp] = ss;
.LBB0_1109:
	v_add_u32_e32 v129, s5, v137
	v_mad_i64_i32 v[132:133], s[26:27], v129, s65, v[130:131]
	global_load_dwordx4 v[138:141], v[132:133], off
	v_add_u32_e32 v164, 8, v129
	v_mad_i64_i32 v[164:165], s[26:27], v164, s65, v[130:131]
	global_load_dwordx4 v[152:155], v[164:165], off
	v_add_u32_e32 v166, 16, v129
	v_mad_i64_i32 v[166:167], s[26:27], v166, s65, v[130:131]
	v_add_u32_e32 v168, 24, v129
	global_load_dwordx4 v[156:159], v[166:167], off
	v_mad_i64_i32 v[168:169], s[26:27], v168, s65, v[130:131]
	global_load_dwordx4 v[160:163], v[168:169], off
	s_add_i32 s5, s5, 32
	s_cmp_eq_u32 s5, 64
	s_waitcnt vmcnt(3)
	v_lshlrev_b32_e32 v142, 16, v138
	v_and_b32_e32 v143, 0xffff0000, v138
	v_lshlrev_b32_e32 v144, 16, v139
	v_and_b32_e32 v145, 0xffff0000, v139
	v_lshlrev_b32_e32 v138, 16, v140
	v_and_b32_e32 v139, 0xffff0000, v140
	v_lshlrev_b32_e32 v140, 16, v141
	v_and_b32_e32 v141, 0xffff0000, v141
	ds_write_b128 v128, v[138:141] offset:16
	ds_write_b128 v128, v[142:145]
	s_waitcnt vmcnt(2)
	v_lshlrev_b32_e32 v142, 16, v152
	v_and_b32_e32 v143, 0xffff0000, v152
	v_lshlrev_b32_e32 v144, 16, v153
	v_and_b32_e32 v145, 0xffff0000, v153
	v_lshlrev_b32_e32 v138, 16, v154
	v_and_b32_e32 v139, 0xffff0000, v154
	v_lshlrev_b32_e32 v140, 16, v155
	v_and_b32_e32 v141, 0xffff0000, v155
	ds_write_b128 v128, v[138:141] offset:2192
	ds_write_b128 v128, v[142:145] offset:2176
	s_waitcnt vmcnt(1)
	v_lshlrev_b32_e32 v142, 16, v156
	v_and_b32_e32 v143, 0xffff0000, v156
	v_lshlrev_b32_e32 v144, 16, v157
	v_and_b32_e32 v145, 0xffff0000, v157
	v_lshlrev_b32_e32 v138, 16, v158
	v_and_b32_e32 v139, 0xffff0000, v158
	v_lshlrev_b32_e32 v140, 16, v159
	v_and_b32_e32 v141, 0xffff0000, v159
	ds_write_b128 v128, v[138:141] offset:4368
	ds_write_b128 v128, v[142:145] offset:4352
	s_waitcnt vmcnt(0)
	v_lshlrev_b32_e32 v142, 16, v160
	v_and_b32_e32 v143, 0xffff0000, v160
	v_lshlrev_b32_e32 v144, 16, v161
	v_and_b32_e32 v145, 0xffff0000, v161
	v_lshlrev_b32_e32 v138, 16, v162
	v_and_b32_e32 v139, 0xffff0000, v162
	v_lshlrev_b32_e32 v140, 16, v163
	v_and_b32_e32 v141, 0xffff0000, v163
	ds_write_b128 v128, v[142:145] offset:6528
	ds_write_b128 v128, v[138:141] offset:6544
	v_add_u32_e32 v128, 0x2200, v128
	s_cbranch_scc0 .LBB0_1109
	ds_read_b128 v[138:141], v236
	ds_read_b128 v[142:145], v236 offset:32
	v_and_b32_e32 v129, 64, v231
	v_xor_b32_e32 v128, 32, v231
	v_add_u32_e32 v129, 64, v129
	s_waitcnt lgkmcnt(1)
	v_pk_add_f32 v[138:139], v[112:113], v[138:139]
	v_pk_add_f32 v[140:141], v[114:115], v[140:141]
	ds_write_b128 v236, v[138:141]
	v_pk_mul_f32 v[114:115], v[138:139], v[138:139]
	v_pk_mul_f32 v[112:113], v[140:141], v[140:141]
	s_waitcnt lgkmcnt(1)
	v_pk_add_f32 v[138:139], v[116:117], v[142:143]
	v_pk_add_f32 v[140:141], v[118:119], v[144:145]
	ds_write_b128 v236, v[138:141] offset:32
	v_pk_mul_f32 v[118:119], v[138:139], v[138:139]
	v_pk_mul_f32 v[116:117], v[140:141], v[140:141]
	ds_read_b128 v[138:141], v236 offset:64
	v_cmp_lt_i32_e32 vcc, v128, v129
	v_lshl_add_u32 v132, s4, 8, v219
	s_lshl_b32 s4, s9, 2
	v_cndmask_b32_e32 v128, v231, v128, vcc
	s_waitcnt lgkmcnt(0)
	v_pk_add_f32 v[138:139], v[120:121], v[138:139]
	v_pk_add_f32 v[140:141], v[122:123], v[140:141]
	ds_write_b128 v236, v[138:141] offset:64
	v_pk_mul_f32 v[122:123], v[138:139], v[138:139]
	v_pk_mul_f32 v[120:121], v[140:141], v[140:141]
	ds_read_b128 v[138:141], v236 offset:96
	v_lshlrev_b32_e32 v136, 2, v128
	s_ashr_i32 s5, s4, 31
	v_or_b32_e32 v132, v132, v218
	v_lshl_add_u64 v[128:129], s[4:5], 2, v[198:199]
	s_waitcnt lgkmcnt(0)
	v_pk_add_f32 v[124:125], v[124:125], v[138:139]
	v_pk_add_f32 v[126:127], v[126:127], v[140:141]
	ds_write_b128 v236, v[124:127] offset:96
	v_pk_mul_f32 v[138:139], v[124:125], v[124:125]
	v_pk_mul_f32 v[140:141], v[126:127], v[126:127]
	ds_read_b128 v[124:127], v236 offset:128
	v_ashrrev_i32_e32 v133, 31, v132
	s_waitcnt lgkmcnt(0)
	v_pk_add_f32 v[96:97], v[96:97], v[124:125]
	v_pk_add_f32 v[98:99], v[98:99], v[126:127]
	ds_write_b128 v236, v[96:99] offset:128
	v_pk_mul_f32 v[124:125], v[96:97], v[96:97]
	v_pk_mul_f32 v[126:127], v[98:99], v[98:99]
	ds_read_b128 v[96:99], v236 offset:160
	s_waitcnt lgkmcnt(0)
	v_pk_add_f32 v[96:97], v[100:101], v[96:97]
	v_pk_add_f32 v[98:99], v[102:103], v[98:99]
	ds_write_b128 v236, v[96:99] offset:160
	v_pk_mul_f32 v[100:101], v[96:97], v[96:97]
	v_pk_mul_f32 v[102:103], v[98:99], v[98:99]
	ds_read_b128 v[96:99], v236 offset:192
	v_add_f32_e32 v100, v100, v101
	v_add_f32_e32 v100, v102, v100
	v_add_f32_e32 v100, v103, v100
	s_waitcnt lgkmcnt(0)
	v_pk_add_f32 v[96:97], v[104:105], v[96:97]
	v_pk_add_f32 v[98:99], v[106:107], v[98:99]
	ds_write_b128 v236, v[96:99] offset:192
	v_pk_mul_f32 v[104:105], v[96:97], v[96:97]
	v_pk_mul_f32 v[106:107], v[98:99], v[98:99]
	ds_read_b128 v[96:99], v236 offset:224
	v_add_f32_e32 v101, v104, v105
	v_add_f32_e32 v101, v106, v101
	v_add_f32_e32 v101, v107, v101
	s_waitcnt lgkmcnt(0)
	v_pk_add_f32 v[96:97], v[108:109], v[96:97]
	v_add_f32_e32 v108, v118, v119
	v_add_f32_e32 v109, v114, v115
	v_add_f32_e32 v108, v116, v108
	v_add_f32_e32 v109, v112, v109
	v_add_f32_e32 v108, v117, v108
	v_add_f32_e32 v109, v113, v109
	v_add_f32_e32 v108, v109, v108
	v_add_f32_e32 v109, v122, v123
	v_add_f32_e32 v109, v120, v109
	v_add_f32_e32 v109, v121, v109
	v_add_f32_e32 v108, v108, v109
	v_add_f32_e32 v109, v138, v139
	v_add_f32_e32 v109, v140, v109
	v_add_f32_e32 v109, v141, v109
	v_add_f32_e32 v108, v108, v109
	v_add_f32_e32 v109, v124, v125
	v_pk_add_f32 v[98:99], v[110:111], v[98:99]
	v_add_f32_e32 v109, v126, v109
	ds_write_b128 v236, v[96:99] offset:224
	v_pk_mul_f32 v[96:97], v[96:97], v[96:97]
	v_add_f32_e32 v109, v127, v109
	v_pk_mul_f32 v[98:99], v[98:99], v[98:99]
	v_add_f32_e32 v108, v108, v109
	v_add_f32_e32 v96, v96, v97
	v_add_f32_e32 v100, v108, v100
	v_add_f32_e32 v96, v98, v96
	v_add_f32_e32 v100, v100, v101
	v_add_f32_e32 v96, v99, v96
	v_add_f32_e32 v96, v100, v96
	ds_bpermute_b32 v97, v136, v96
	s_and_saveexec_b64 s[4:5], s[2:3]
	s_cbranch_execz .LBB0_1112
	v_lshlrev_b64 v[98:99], 6, v[132:133]
	v_lshl_add_u64 v[98:99], v[128:129], 0, v[98:99]
	s_waitcnt lgkmcnt(0)
	v_add_f32_e32 v96, v96, v97
	global_store_dword v[98:99], v96, off

; DI float xor32(float v) { return __shfl_xor(v, 32); }
; DI void phase_resid(const P& p, const bf16_t* W, const bf16_t* X, int K, bf16_t* sm, const Geo& ge, bool last) {
;     ...
;     for (int cp = 0; cp < 2; ++cp) {
; #pragma unroll 4
;       for (int it = 0; it < 8; ++it) {
;         const int row = it * 8 + (lane >> 3), c8 = (lane & 7) * 8;
;         const u32x4 raw = *(const u32x4*)(xb + (size_t)(m0w + row) * LDK1 + n0w + cp * 64 + c8);
;         float* d = stg + row * 68 + c8;
;         *(float4*)(d) = make_float4(__uint_as_float(raw[0] << 16), __uint_as_float(raw[0] & 0xffff0000u),
;                                     __uint_as_float(raw[1] << 16), __uint_as_float(raw[1] & 0xffff0000u));
;         *(float4*)(d + 4) = make_float4(__uint_as_float(raw[2] << 16), __uint_as_float(raw[2] & 0xffff0000u),
;                                         __uint_as_float(raw[3] << 16), __uint_as_float(raw[3] & 0xffff0000u));
;       }
; #pragma unroll
;       for (int mt = 0; mt < 2; ++mt) {
;         float ss = 0.f;
; #pragma unroll
;         for (int nh = 0; nh < 2; ++nh)
; #pragma unroll
;           for (int qd = 0; qd < 4; ++qd) {
;             const int nt = cp * 2 + nh;
;             float4* sp = (float4*)(stg + (mt * 32 + lr) * 68 + nh * 32 + 8 * qd + 4 * lh);
;             float4 v = *sp;
;             v.x += acc[nt][mt][4 * qd]; v.y += acc[nt][mt][4 * qd + 1]; v.z += acc[nt][mt][4 * qd + 2]; v.w += acc[nt][mt][4 * qd + 3];
;             *sp = v;
;             ss += v.x * v.x + v.y * v.y + v.z * v.z + v.w * v.w;
;           }
;         ss += xor32(ss);
;         if (lh == 0) part[(size_t)(m0w + mt * 32 + lr) * 16 + nt_ * 4 + wn * 2 + cp] = ss;
.LBB0_1117:
	v_add_u32_e32 v78, s4, v137
	v_mad_i64_i32 v[70:71], s[26:27], v78, s65, v[130:131]
	global_load_dwordx4 v[70:73], v[70:71], off offset:128
	v_add_u32_e32 v164, 8, v78
	v_mad_i64_i32 v[164:165], s[26:27], v164, s65, v[130:131]
	global_load_dwordx4 v[152:155], v[164:165], off offset:128
	v_add_u32_e32 v166, 16, v78
	v_mad_i64_i32 v[166:167], s[26:27], v166, s65, v[130:131]
	global_load_dwordx4 v[156:159], v[166:167], off offset:128
	v_add_u32_e32 v168, 24, v78
	v_mad_i64_i32 v[168:169], s[26:27], v168, s65, v[130:131]
	global_load_dwordx4 v[160:163], v[168:169], off offset:128
	s_add_i32 s4, s4, 32
	s_cmp_lg_u32 s4, 64
	s_waitcnt vmcnt(3)
	v_lshlrev_b32_e32 v74, 16, v70
	v_and_b32_e32 v75, 0xffff0000, v70
	v_lshlrev_b32_e32 v76, 16, v71
	v_and_b32_e32 v77, 0xffff0000, v71
	v_lshlrev_b32_e32 v70, 16, v72
	v_and_b32_e32 v71, 0xffff0000, v72
	v_lshlrev_b32_e32 v72, 16, v73
	v_and_b32_e32 v73, 0xffff0000, v73
	ds_write_b128 v69, v[70:73] offset:16
	ds_write_b128 v69, v[74:77]
	s_waitcnt vmcnt(2)
	v_lshlrev_b32_e32 v74, 16, v152
	v_and_b32_e32 v75, 0xffff0000, v152
	v_lshlrev_b32_e32 v76, 16, v153
	v_and_b32_e32 v77, 0xffff0000, v153
	v_lshlrev_b32_e32 v70, 16, v154
	v_and_b32_e32 v71, 0xffff0000, v154
	v_lshlrev_b32_e32 v72, 16, v155
	v_and_b32_e32 v73, 0xffff0000, v155
	ds_write_b128 v69, v[70:73] offset:2192
	ds_write_b128 v69, v[74:77] offset:2176
	s_waitcnt vmcnt(1)
	v_lshlrev_b32_e32 v74, 16, v156
	v_and_b32_e32 v75, 0xffff0000, v156
	v_lshlrev_b32_e32 v76, 16, v157
	v_and_b32_e32 v77, 0xffff0000, v157
	v_lshlrev_b32_e32 v70, 16, v158
	v_and_b32_e32 v71, 0xffff0000, v158
	v_lshlrev_b32_e32 v72, 16, v159
	v_and_b32_e32 v73, 0xffff0000, v159
	ds_write_b128 v69, v[70:73] offset:4368
	ds_write_b128 v69, v[74:77] offset:4352
	s_waitcnt vmcnt(0)
	v_lshlrev_b32_e32 v74, 16, v160
	v_and_b32_e32 v75, 0xffff0000, v160
	v_lshlrev_b32_e32 v76, 16, v161
	v_and_b32_e32 v77, 0xffff0000, v161
	v_lshlrev_b32_e32 v70, 16, v162
	v_and_b32_e32 v71, 0xffff0000, v162
	v_lshlrev_b32_e32 v72, 16, v163
	v_and_b32_e32 v73, 0xffff0000, v163
	ds_write_b128 v69, v[74:77] offset:6528
	ds_write_b128 v69, v[70:73] offset:6544
	v_add_u32_e32 v69, 0x2200, v69
	s_cbranch_scc1 .LBB0_1117
	ds_read_b128 v[70:73], v236
	ds_read_b128 v[74:77], v236 offset:32
	s_waitcnt lgkmcnt(1)
	v_pk_add_f32 v[70:71], v[48:49], v[70:71]
	v_pk_add_f32 v[72:73], v[50:51], v[72:73]
	ds_write_b128 v236, v[70:73]
	v_pk_mul_f32 v[50:51], v[70:71], v[70:71]
	v_pk_mul_f32 v[48:49], v[72:73], v[72:73]
	s_waitcnt lgkmcnt(1)
	v_pk_add_f32 v[70:71], v[52:53], v[74:75]
	v_pk_add_f32 v[72:73], v[54:55], v[76:77]
	ds_write_b128 v236, v[70:73] offset:32
	v_pk_mul_f32 v[54:55], v[70:71], v[70:71]
	v_pk_mul_f32 v[52:53], v[72:73], v[72:73]
	ds_read_b128 v[70:73], v236 offset:64
	s_waitcnt lgkmcnt(0)
	v_pk_add_f32 v[70:71], v[56:57], v[70:71]
	v_pk_add_f32 v[72:73], v[58:59], v[72:73]
	ds_write_b128 v236, v[70:73] offset:64
	v_pk_mul_f32 v[58:59], v[70:71], v[70:71]
	v_pk_mul_f32 v[56:57], v[72:73], v[72:73]
	ds_read_b128 v[70:73], v236 offset:96
	s_waitcnt lgkmcnt(0)
	v_pk_add_f32 v[60:61], v[60:61], v[70:71]
	v_pk_add_f32 v[62:63], v[62:63], v[72:73]
	ds_write_b128 v236, v[60:63] offset:96
	v_pk_mul_f32 v[70:71], v[60:61], v[60:61]
	v_pk_mul_f32 v[72:73], v[62:63], v[62:63]
	ds_read_b128 v[60:63], v236 offset:128
	s_waitcnt lgkmcnt(0)
	v_pk_add_f32 v[32:33], v[32:33], v[60:61]
	v_pk_add_f32 v[34:35], v[34:35], v[62:63]
	ds_write_b128 v236, v[32:35] offset:128
	v_pk_mul_f32 v[60:61], v[32:33], v[32:33]
	v_pk_mul_f32 v[62:63], v[34:35], v[34:35]
	ds_read_b128 v[32:35], v236 offset:160
	s_waitcnt lgkmcnt(0)
	v_pk_add_f32 v[32:33], v[36:37], v[32:33]
	v_pk_add_f32 v[34:35], v[38:39], v[34:35]
	ds_write_b128 v236, v[32:35] offset:160
	v_pk_mul_f32 v[36:37], v[32:33], v[32:33]
	v_pk_mul_f32 v[38:39], v[34:35], v[34:35]
	ds_read_b128 v[32:35], v236 offset:192
	v_add_f32_e32 v36, v36, v37
	v_add_f32_e32 v36, v38, v36
	v_add_f32_e32 v36, v39, v36
	s_waitcnt lgkmcnt(0)
	v_pk_add_f32 v[32:33], v[40:41], v[32:33]
	v_pk_add_f32 v[34:35], v[42:43], v[34:35]
	ds_write_b128 v236, v[32:35] offset:192
	v_pk_mul_f32 v[40:41], v[32:33], v[32:33]
	v_pk_mul_f32 v[42:43], v[34:35], v[34:35]
	ds_read_b128 v[32:35], v236 offset:224
	v_add_f32_e32 v37, v40, v41
	v_add_f32_e32 v37, v42, v37
	v_add_f32_e32 v37, v43, v37
	s_waitcnt lgkmcnt(0)
	v_pk_add_f32 v[32:33], v[44:45], v[32:33]
	v_add_f32_e32 v44, v54, v55
	v_add_f32_e32 v45, v50, v51
	v_add_f32_e32 v44, v52, v44
	v_add_f32_e32 v45, v48, v45
	v_add_f32_e32 v44, v53, v44
	v_add_f32_e32 v45, v49, v45
	v_add_f32_e32 v44, v45, v44
	v_add_f32_e32 v45, v58, v59
	v_add_f32_e32 v45, v56, v45
	v_add_f32_e32 v45, v57, v45
	v_add_f32_e32 v44, v44, v45
	v_add_f32_e32 v45, v70, v71
	v_add_f32_e32 v45, v72, v45
	v_add_f32_e32 v45, v73, v45
	v_add_f32_e32 v44, v44, v45
	v_add_f32_e32 v45, v60, v61
	v_pk_add_f32 v[34:35], v[46:47], v[34:35]
	v_add_f32_e32 v45, v62, v45
	ds_write_b128 v236, v[32:35] offset:224
	v_pk_mul_f32 v[32:33], v[32:33], v[32:33]
	v_add_f32_e32 v45, v63, v45
	v_pk_mul_f32 v[34:35], v[34:35], v[34:35]
	v_add_f32_e32 v44, v44, v45
	v_add_f32_e32 v32, v32, v33
	v_add_f32_e32 v36, v44, v36
	v_add_f32_e32 v32, v34, v32
	v_add_f32_e32 v36, v36, v37
	v_add_f32_e32 v32, v35, v32
	v_add_f32_e32 v32, v36, v32
	ds_bpermute_b32 v33, v136, v32
	s_and_saveexec_b64 s[4:5], s[2:3]
	s_cbranch_execz .LBB0_1120
	v_lshlrev_b64 v[34:35], 6, v[132:133]
	v_lshl_add_u64 v[34:35], v[128:129], 0, v[34:35]
	s_waitcnt lgkmcnt(0)
	v_add_f32_e32 v32, v32, v33
	global_store_dword v[34:35], v32, off offset:4

; DI float xor32(float v) { return __shfl_xor(v, 32); }
; DI void phase_resid(const P& p, const bf16_t* W, const bf16_t* X, int K, bf16_t* sm, const Geo& ge, bool last) {
;     ...
;       for (int it = 0; it < 8; ++it) {
;         const int row = it * 8 + (lane >> 3), c8 = (lane & 7) * 8;
;         const u32x4 raw = *(const u32x4*)(xb + (size_t)(m0w + row) * LDK1 + n0w + cp * 64 + c8);
;         float* d = stg + row * 68 + c8;
;         *(float4*)(d) = make_float4(__uint_as_float(raw[0] << 16), __uint_as_float(raw[0] & 0xffff0000u),
;                                     __uint_as_float(raw[1] << 16), __uint_as_float(raw[1] & 0xffff0000u));
;         *(float4*)(d + 4) = make_float4(__uint_as_float(raw[2] << 16), __uint_as_float(raw[2] & 0xffff0000u),
;                                         __uint_as_float(raw[3] << 16), __uint_as_float(raw[3] & 0xffff0000u));
;       }
; #pragma unroll
;       for (int mt = 0; mt < 2; ++mt) {
;         float ss = 0.f;
; #pragma unroll
;         for (int nh = 0; nh < 2; ++nh)
; #pragma unroll
;           for (int qd = 0; qd < 4; ++qd) {
;             const int nt = cp * 2 + nh;
;             float4* sp = (float4*)(stg + (mt * 32 + lr) * 68 + nh * 32 + 8 * qd + 4 * lh);
;             float4 v = *sp;
;             v.x += acc[nt][mt][4 * qd]; v.y += acc[nt][mt][4 * qd + 1]; v.z += acc[nt][mt][4 * qd + 2]; v.w += acc[nt][mt][4 * qd + 3];
;             *sp = v;
;             ss += v.x * v.x + v.y * v.y + v.z * v.z + v.w * v.w;
;           }
;         ss += xor32(ss);
;         if (lh == 0) part[(size_t)(m0w + mt * 32 + lr) * 16 + nt_ * 4 + wn * 2 + cp] = ss;
.LBB0_1166:
	v_add_u32_e32 v131, s5, v137
	v_mad_i64_i32 v[134:135], s[28:29], v131, s65, v[132:133]
	global_load_dwordx4 v[138:141], v[134:135], off
	v_add_u32_e32 v164, 8, v131
	v_mad_i64_i32 v[164:165], s[28:29], v164, s65, v[132:133]
	global_load_dwordx4 v[152:155], v[164:165], off
	v_add_u32_e32 v166, 16, v131
	v_mad_i64_i32 v[166:167], s[28:29], v166, s65, v[132:133]
	v_add_u32_e32 v168, 24, v131
	global_load_dwordx4 v[156:159], v[166:167], off
	v_mad_i64_i32 v[168:169], s[28:29], v168, s65, v[132:133]
	global_load_dwordx4 v[160:163], v[168:169], off
	s_add_i32 s5, s5, 32
	s_cmp_eq_u32 s5, 64
	s_waitcnt vmcnt(3)
	v_lshlrev_b32_e32 v142, 16, v138
	v_and_b32_e32 v143, 0xffff0000, v138
	v_lshlrev_b32_e32 v144, 16, v139
	v_and_b32_e32 v145, 0xffff0000, v139
	v_lshlrev_b32_e32 v138, 16, v140
	v_and_b32_e32 v139, 0xffff0000, v140
	v_lshlrev_b32_e32 v140, 16, v141
	v_and_b32_e32 v141, 0xffff0000, v141
	ds_write_b128 v130, v[138:141] offset:16
	ds_write_b128 v130, v[142:145]
	s_waitcnt vmcnt(2)
	v_lshlrev_b32_e32 v142, 16, v152
	v_and_b32_e32 v143, 0xffff0000, v152
	v_lshlrev_b32_e32 v144, 16, v153
	v_and_b32_e32 v145, 0xffff0000, v153
	v_lshlrev_b32_e32 v138, 16, v154
	v_and_b32_e32 v139, 0xffff0000, v154
	v_lshlrev_b32_e32 v140, 16, v155
	v_and_b32_e32 v141, 0xffff0000, v155
	ds_write_b128 v130, v[138:141] offset:2192
	ds_write_b128 v130, v[142:145] offset:2176
	s_waitcnt vmcnt(1)
	v_lshlrev_b32_e32 v142, 16, v156
	v_and_b32_e32 v143, 0xffff0000, v156
	v_lshlrev_b32_e32 v144, 16, v157
	v_and_b32_e32 v145, 0xffff0000, v157
	v_lshlrev_b32_e32 v138, 16, v158
	v_and_b32_e32 v139, 0xffff0000, v158
	v_lshlrev_b32_e32 v140, 16, v159
	v_and_b32_e32 v141, 0xffff0000, v159
	ds_write_b128 v130, v[138:141] offset:4368
	ds_write_b128 v130, v[142:145] offset:4352
	s_waitcnt vmcnt(0)
	v_lshlrev_b32_e32 v142, 16, v160
	v_and_b32_e32 v143, 0xffff0000, v160
	v_lshlrev_b32_e32 v144, 16, v161
	v_and_b32_e32 v145, 0xffff0000, v161
	v_lshlrev_b32_e32 v138, 16, v162
	v_and_b32_e32 v139, 0xffff0000, v162
	v_lshlrev_b32_e32 v140, 16, v163
	v_and_b32_e32 v141, 0xffff0000, v163
	ds_write_b128 v130, v[142:145] offset:6528
	ds_write_b128 v130, v[138:141] offset:6544
	v_add_u32_e32 v130, 0x2200, v130
	s_cbranch_scc0 .LBB0_1166
	ds_read_b128 v[138:141], v238
	ds_read_b128 v[142:145], v238 offset:32
	v_and_b32_e32 v131, 64, v231
	v_xor_b32_e32 v130, 32, v231
	v_add_u32_e32 v131, 64, v131
	s_waitcnt lgkmcnt(1)
	v_pk_add_f32 v[138:139], v[112:113], v[138:139]
	v_pk_add_f32 v[140:141], v[114:115], v[140:141]
	ds_write_b128 v238, v[138:141]
	v_pk_mul_f32 v[114:115], v[138:139], v[138:139]
	v_pk_mul_f32 v[112:113], v[140:141], v[140:141]
	s_waitcnt lgkmcnt(1)
	v_pk_add_f32 v[138:139], v[116:117], v[142:143]
	v_pk_add_f32 v[140:141], v[118:119], v[144:145]
	ds_write_b128 v238, v[138:141] offset:32
	v_pk_mul_f32 v[118:119], v[138:139], v[138:139]
	v_pk_mul_f32 v[116:117], v[140:141], v[140:141]
	ds_read_b128 v[138:141], v238 offset:64
	v_cmp_lt_i32_e32 vcc, v130, v131
	v_lshl_add_u32 v134, s4, 8, v236
	s_lshl_b32 s4, s8, 2
	v_cndmask_b32_e32 v130, v231, v130, vcc
	s_waitcnt lgkmcnt(0)
	v_pk_add_f32 v[138:139], v[120:121], v[138:139]
	v_pk_add_f32 v[140:141], v[122:123], v[140:141]
	ds_write_b128 v238, v[138:141] offset:64
	v_pk_mul_f32 v[122:123], v[138:139], v[138:139]
	v_pk_mul_f32 v[120:121], v[140:141], v[140:141]
	ds_read_b128 v[138:141], v238 offset:96
	v_lshlrev_b32_e32 v136, 2, v130
	s_ashr_i32 s5, s4, 31
	v_or_b32_e32 v134, v134, v235
	v_lshl_add_u64 v[130:131], s[4:5], 2, v[198:199]
	s_waitcnt lgkmcnt(0)
	v_pk_add_f32 v[124:125], v[124:125], v[138:139]
	v_pk_add_f32 v[126:127], v[126:127], v[140:141]
	ds_write_b128 v238, v[124:127] offset:96
	v_pk_mul_f32 v[138:139], v[124:125], v[124:125]
	v_pk_mul_f32 v[140:141], v[126:127], v[126:127]
	ds_read_b128 v[124:127], v238 offset:128
	v_ashrrev_i32_e32 v135, 31, v134
	s_waitcnt lgkmcnt(0)
	v_pk_add_f32 v[96:97], v[96:97], v[124:125]
	v_pk_add_f32 v[98:99], v[98:99], v[126:127]
	ds_write_b128 v238, v[96:99] offset:128
	v_pk_mul_f32 v[124:125], v[96:97], v[96:97]
	v_pk_mul_f32 v[126:127], v[98:99], v[98:99]
	ds_read_b128 v[96:99], v238 offset:160
	s_waitcnt lgkmcnt(0)
	v_pk_add_f32 v[96:97], v[100:101], v[96:97]
	v_pk_add_f32 v[98:99], v[102:103], v[98:99]
	ds_write_b128 v238, v[96:99] offset:160
	v_pk_mul_f32 v[100:101], v[96:97], v[96:97]
	v_pk_mul_f32 v[102:103], v[98:99], v[98:99]
	ds_read_b128 v[96:99], v238 offset:192
	v_add_f32_e32 v100, v100, v101
	v_add_f32_e32 v100, v102, v100
	v_add_f32_e32 v100, v103, v100
	s_waitcnt lgkmcnt(0)
	v_pk_add_f32 v[96:97], v[104:105], v[96:97]
	v_pk_add_f32 v[98:99], v[106:107], v[98:99]
	ds_write_b128 v238, v[96:99] offset:192
	v_pk_mul_f32 v[104:105], v[96:97], v[96:97]
	v_pk_mul_f32 v[106:107], v[98:99], v[98:99]
	ds_read_b128 v[96:99], v238 offset:224
	v_add_f32_e32 v101, v104, v105
	v_add_f32_e32 v101, v106, v101
	v_add_f32_e32 v101, v107, v101
	s_waitcnt lgkmcnt(0)
	v_pk_add_f32 v[96:97], v[108:109], v[96:97]
	v_add_f32_e32 v108, v118, v119
	v_add_f32_e32 v109, v114, v115
	v_add_f32_e32 v108, v116, v108
	v_add_f32_e32 v109, v112, v109
	v_add_f32_e32 v108, v117, v108
	v_add_f32_e32 v109, v113, v109
	v_add_f32_e32 v108, v109, v108
	v_add_f32_e32 v109, v122, v123
	v_add_f32_e32 v109, v120, v109
	v_add_f32_e32 v109, v121, v109
	v_add_f32_e32 v108, v108, v109
	v_add_f32_e32 v109, v138, v139
	v_add_f32_e32 v109, v140, v109
	v_add_f32_e32 v109, v141, v109
	v_add_f32_e32 v108, v108, v109
	v_add_f32_e32 v109, v124, v125
	v_pk_add_f32 v[98:99], v[110:111], v[98:99]
	v_add_f32_e32 v109, v126, v109
	ds_write_b128 v238, v[96:99] offset:224
	v_pk_mul_f32 v[96:97], v[96:97], v[96:97]
	v_add_f32_e32 v109, v127, v109
	v_pk_mul_f32 v[98:99], v[98:99], v[98:99]
	v_add_f32_e32 v108, v108, v109
	v_add_f32_e32 v96, v96, v97
	v_add_f32_e32 v100, v108, v100
	v_add_f32_e32 v96, v98, v96
	v_add_f32_e32 v100, v100, v101
	v_add_f32_e32 v96, v99, v96
	v_add_f32_e32 v96, v100, v96
	ds_bpermute_b32 v97, v136, v96
	s_and_saveexec_b64 s[4:5], s[2:3]
	s_cbranch_execz .LBB0_1169
	v_lshlrev_b64 v[98:99], 6, v[134:135]
	v_lshl_add_u64 v[98:99], v[130:131], 0, v[98:99]
	s_waitcnt lgkmcnt(0)
	v_add_f32_e32 v96, v96, v97
	global_store_dword v[98:99], v96, off

; DI float xor32(float v) { return __shfl_xor(v, 32); }
; DI void phase_resid(const P& p, const bf16_t* W, const bf16_t* X, int K, bf16_t* sm, const Geo& ge, bool last) {
;     ...
;       for (int it = 0; it < 8; ++it) {
;         const int row = it * 8 + (lane >> 3), c8 = (lane & 7) * 8;
;         const u32x4 raw = *(const u32x4*)(xb + (size_t)(m0w + row) * LDK1 + n0w + cp * 64 + c8);
;         float* d = stg + row * 68 + c8;
;         *(float4*)(d) = make_float4(__uint_as_float(raw[0] << 16), __uint_as_float(raw[0] & 0xffff0000u),
;                                     __uint_as_float(raw[1] << 16), __uint_as_float(raw[1] & 0xffff0000u));
;         *(float4*)(d + 4) = make_float4(__uint_as_float(raw[2] << 16), __uint_as_float(raw[2] & 0xffff0000u),
;                                         __uint_as_float(raw[3] << 16), __uint_as_float(raw[3] & 0xffff0000u));
;       }
; #pragma unroll
;       for (int mt = 0; mt < 2; ++mt) {
;         float ss = 0.f;
; #pragma unroll
;         for (int nh = 0; nh < 2; ++nh)
; #pragma unroll
;           for (int qd = 0; qd < 4; ++qd) {
;             const int nt = cp * 2 + nh;
;             float4* sp = (float4*)(stg + (mt * 32 + lr) * 68 + nh * 32 + 8 * qd + 4 * lh);
;             float4 v = *sp;
;             v.x += acc[nt][mt][4 * qd]; v.y += acc[nt][mt][4 * qd + 1]; v.z += acc[nt][mt][4 * qd + 2]; v.w += acc[nt][mt][4 * qd + 3];
;             *sp = v;
;             ss += v.x * v.x + v.y * v.y + v.z * v.z + v.w * v.w;
;           }
;         ss += xor32(ss);
;         if (lh == 0) part[(size_t)(m0w + mt * 32 + lr) * 16 + nt_ * 4 + wn * 2 + cp] = ss;
.LBB0_1183:
	v_add_u32_e32 v65, s8, v137
	v_mad_i64_i32 v[66:67], s[28:29], v65, s65, v[132:133]
	global_load_dwordx4 v[72:75], v[66:67], off offset:128
	v_add_u32_e32 v164, 8, v65
	v_mad_i64_i32 v[164:165], s[28:29], v164, s65, v[132:133]
	global_load_dwordx4 v[152:155], v[164:165], off offset:128
	v_add_u32_e32 v166, 16, v65
	v_mad_i64_i32 v[166:167], s[28:29], v166, s65, v[132:133]
	v_add_u32_e32 v168, 24, v65
	global_load_dwordx4 v[156:159], v[166:167], off offset:128
	v_mad_i64_i32 v[168:169], s[28:29], v168, s65, v[132:133]
	global_load_dwordx4 v[160:163], v[168:169], off offset:128
	s_add_i32 s8, s8, 32
	s_cmp_lg_u32 s8, 64
	s_waitcnt vmcnt(3)
	v_lshlrev_b32_e32 v80, 16, v72
	v_and_b32_e32 v81, 0xffff0000, v72
	v_lshlrev_b32_e32 v82, 16, v73
	v_and_b32_e32 v83, 0xffff0000, v73
	v_lshlrev_b32_e32 v72, 16, v74
	v_and_b32_e32 v73, 0xffff0000, v74
	v_lshlrev_b32_e32 v74, 16, v75
	v_and_b32_e32 v75, 0xffff0000, v75
	ds_write_b128 v64, v[72:75] offset:16
	ds_write_b128 v64, v[80:83]
	s_waitcnt vmcnt(2)
	v_lshlrev_b32_e32 v80, 16, v152
	v_and_b32_e32 v81, 0xffff0000, v152
	v_lshlrev_b32_e32 v82, 16, v153
	v_and_b32_e32 v83, 0xffff0000, v153
	v_lshlrev_b32_e32 v72, 16, v154
	v_and_b32_e32 v73, 0xffff0000, v154
	v_lshlrev_b32_e32 v74, 16, v155
	v_and_b32_e32 v75, 0xffff0000, v155
	ds_write_b128 v64, v[72:75] offset:2192
	ds_write_b128 v64, v[80:83] offset:2176
	s_waitcnt vmcnt(1)
	v_lshlrev_b32_e32 v80, 16, v156
	v_and_b32_e32 v81, 0xffff0000, v156
	v_lshlrev_b32_e32 v82, 16, v157
	v_and_b32_e32 v83, 0xffff0000, v157
	v_lshlrev_b32_e32 v72, 16, v158
	v_and_b32_e32 v73, 0xffff0000, v158
	v_lshlrev_b32_e32 v74, 16, v159
	v_and_b32_e32 v75, 0xffff0000, v159
	ds_write_b128 v64, v[72:75] offset:4368
	ds_write_b128 v64, v[80:83] offset:4352
	s_waitcnt vmcnt(0)
	v_lshlrev_b32_e32 v80, 16, v160
	v_and_b32_e32 v81, 0xffff0000, v160
	v_lshlrev_b32_e32 v82, 16, v161
	v_and_b32_e32 v83, 0xffff0000, v161
	v_lshlrev_b32_e32 v72, 16, v162
	v_and_b32_e32 v73, 0xffff0000, v162
	v_lshlrev_b32_e32 v74, 16, v163
	v_and_b32_e32 v75, 0xffff0000, v163
	ds_write_b128 v64, v[80:83] offset:6528
	ds_write_b128 v64, v[72:75] offset:6544
	v_add_u32_e32 v64, 0x2200, v64
	s_cbranch_scc1 .LBB0_1183
	ds_read_b128 v[64:67], v238
	ds_read_b128 v[72:75], v238 offset:32
	s_waitcnt lgkmcnt(1)
	v_pk_add_f32 v[64:65], v[48:49], v[64:65]
	v_pk_add_f32 v[66:67], v[50:51], v[66:67]
	ds_write_b128 v238, v[64:67]
	v_pk_mul_f32 v[50:51], v[64:65], v[64:65]
	v_pk_mul_f32 v[48:49], v[66:67], v[66:67]
	s_waitcnt lgkmcnt(1)
	v_pk_add_f32 v[64:65], v[52:53], v[72:73]
	v_pk_add_f32 v[66:67], v[54:55], v[74:75]
	ds_write_b128 v238, v[64:67] offset:32
	v_pk_mul_f32 v[54:55], v[64:65], v[64:65]
	v_pk_mul_f32 v[52:53], v[66:67], v[66:67]
	ds_read_b128 v[64:67], v238 offset:64
	s_waitcnt lgkmcnt(0)
	v_pk_add_f32 v[64:65], v[56:57], v[64:65]
	v_pk_add_f32 v[66:67], v[58:59], v[66:67]
	ds_write_b128 v238, v[64:67] offset:64
	v_pk_mul_f32 v[58:59], v[64:65], v[64:65]
	v_pk_mul_f32 v[56:57], v[66:67], v[66:67]
	ds_read_b128 v[64:67], v238 offset:96
	s_waitcnt lgkmcnt(0)
	v_pk_add_f32 v[60:61], v[60:61], v[64:65]
	v_pk_add_f32 v[62:63], v[62:63], v[66:67]
	ds_write_b128 v238, v[60:63] offset:96
	v_pk_mul_f32 v[64:65], v[60:61], v[60:61]
	v_pk_mul_f32 v[66:67], v[62:63], v[62:63]
	ds_read_b128 v[60:63], v238 offset:128
	s_waitcnt lgkmcnt(0)
	v_pk_add_f32 v[32:33], v[32:33], v[60:61]
	v_pk_add_f32 v[34:35], v[34:35], v[62:63]
	ds_write_b128 v238, v[32:35] offset:128
	v_pk_mul_f32 v[60:61], v[32:33], v[32:33]
	v_pk_mul_f32 v[62:63], v[34:35], v[34:35]
	ds_read_b128 v[32:35], v238 offset:160
	s_waitcnt lgkmcnt(0)
	v_pk_add_f32 v[32:33], v[36:37], v[32:33]
	v_pk_add_f32 v[34:35], v[38:39], v[34:35]
	ds_write_b128 v238, v[32:35] offset:160
	v_pk_mul_f32 v[36:37], v[32:33], v[32:33]
	v_pk_mul_f32 v[38:39], v[34:35], v[34:35]
	ds_read_b128 v[32:35], v238 offset:192
	v_add_f32_e32 v36, v36, v37
	v_add_f32_e32 v36, v38, v36
	v_add_f32_e32 v36, v39, v36
	s_waitcnt lgkmcnt(0)
	v_pk_add_f32 v[32:33], v[40:41], v[32:33]
	v_pk_add_f32 v[34:35], v[42:43], v[34:35]
	ds_write_b128 v238, v[32:35] offset:192
	v_pk_mul_f32 v[40:41], v[32:33], v[32:33]
	v_pk_mul_f32 v[42:43], v[34:35], v[34:35]
	ds_read_b128 v[32:35], v238 offset:224
	v_add_f32_e32 v37, v40, v41
	v_add_f32_e32 v37, v42, v37
	v_add_f32_e32 v37, v43, v37
	s_waitcnt lgkmcnt(0)
	v_pk_add_f32 v[32:33], v[44:45], v[32:33]
	v_add_f32_e32 v44, v54, v55
	v_add_f32_e32 v45, v50, v51
	v_add_f32_e32 v44, v52, v44
	v_add_f32_e32 v45, v48, v45
	v_add_f32_e32 v44, v53, v44
	v_add_f32_e32 v45, v49, v45
	v_add_f32_e32 v44, v45, v44
	v_add_f32_e32 v45, v58, v59
	v_add_f32_e32 v45, v56, v45
	v_add_f32_e32 v45, v57, v45
	v_add_f32_e32 v44, v44, v45
	v_add_f32_e32 v45, v64, v65
	v_add_f32_e32 v45, v66, v45
	v_add_f32_e32 v45, v67, v45
	v_add_f32_e32 v44, v44, v45
	v_add_f32_e32 v45, v60, v61
	v_pk_add_f32 v[34:35], v[46:47], v[34:35]
	v_add_f32_e32 v45, v62, v45
	ds_write_b128 v238, v[32:35] offset:224
	v_pk_mul_f32 v[32:33], v[32:33], v[32:33]
	v_add_f32_e32 v45, v63, v45
	v_pk_mul_f32 v[34:35], v[34:35], v[34:35]
	v_add_f32_e32 v44, v44, v45
	v_add_f32_e32 v32, v32, v33
	v_add_f32_e32 v36, v44, v36
	v_add_f32_e32 v32, v34, v32
	v_add_f32_e32 v36, v36, v37
	v_add_f32_e32 v32, v35, v32
	v_add_f32_e32 v32, v36, v32
	ds_bpermute_b32 v33, v136, v32
	s_and_saveexec_b64 s[8:9], s[2:3]
	s_cbranch_execz .LBB0_1186
	v_lshlrev_b64 v[34:35], 6, v[134:135]
	v_lshl_add_u64 v[34:35], v[130:131], 0, v[34:35]
	s_waitcnt lgkmcnt(0)
	v_add_f32_e32 v32, v32, v33
	global_store_dword v[34:35], v32, off offset:4
